# P9: both wave groups run the tile epilogue concurrently (extra barrier for wr=0 at epilogue start, for wr=1 before the next tile; phase-end conditional barrier removed)
# speedup vs baseline: 1.0002x; 1.0002x over previous
.LBB0_1226:
	s_and_b64 vcc, exec, s[26:27]
	s_mov_b32 s28, s16
	s_mov_b32 s42, s69
	s_mov_b64 s[34:35], s[24:25]
	s_mov_b64 s[30:31], s[18:19]
	s_mov_b32 s11, s70
	s_cbranch_vccnz .LBB0_1248
	s_cmpk_gt_u32 s33, 0xff
	s_cbranch_scc0 .Lx1_skip
	s_barrier
.Lx1_skip:
.LBB0_1227:
	v_readlane_b32 s26, v244, 58
	v_readlane_b32 s27, v244, 59
	s_add_i32 s70, s11, 1
	s_mov_b64 s[38:39], 0
	s_and_b64 vcc, exec, s[26:27]
	s_mov_b64 s[36:37], -1
	s_cbranch_vccz .LBB0_1229
	s_mul_i32 s17, s70, s61
	s_mul_hi_u32 s26, s70, s62
	s_add_i32 s17, s26, s17
	s_mul_i32 s26, s70, s62
	s_add_u32 s26, s26, s74
	s_addc_u32 s27, s17, s63
	s_mov_b64 s[36:37], 0
	s_mov_b64 s[38:39], -1

.LBB0_1243:
	ds_read_b128 v[170:173], v162
	ds_read_b128 v[174:177], v162 offset:1024
	ds_read_b128 v[178:181], v162 offset:2048
	ds_read_b128 v[182:185], v162 offset:3072
	s_add_u32 s34, s30, 0xfffc0080
	s_addc_u32 s35, s31, -1
	s_cmp_eq_u32 s41, 12
	s_cselect_b32 s37, s11, s35
	s_cselect_b32 s36, s17, s34
	s_cselect_b32 s35, s29, s40
	s_cselect_b32 s34, s38, s39
	v_lshl_add_u64 v[144:145], s[30:31], 0, v[134:135]
	s_add_i32 m0, s48, 0xc000
	ds_read_b128 v[186:189], v163
	ds_read_b128 v[190:193], v163 offset:1024
	ds_read_b128 v[194:197], v163 offset:2048
	ds_read_b128 v[198:201], v163 offset:3072
	ds_read_b128 v[204:207], v163 offset:4096
	ds_read_b128 v[208:211], v163 offset:5120
	ds_read_b128 v[212:215], v163 offset:6144
	ds_read_b128 v[216:219], v163 offset:7168
	global_load_lds_dwordx4 v[144:145], off
	v_lshl_add_u64 v[144:145], s[30:31], 0, v[136:137]
	s_add_i32 m0, s48, 0xe000
	s_nop 0
	global_load_lds_dwordx4 v[144:145], off
	ds_read_b128 v[220:223], v164
	ds_read_b128 v[224:227], v164 offset:1024
	ds_read_b128 v[228:231], v164 offset:2048
	ds_read_b128 v[232:235], v164 offset:3072
	s_waitcnt lgkmcnt(0)
	s_waitcnt vmcnt(8)
	s_barrier
	s_setprio 1
	v_mfma_f32_16x16x32_bf16 v[124:127], v[170:173], v[186:189], v[124:127]
	v_mfma_f32_16x16x32_bf16 v[120:123], v[178:181], v[186:189], v[120:123]
	v_mfma_f32_16x16x32_bf16 v[112:115], v[170:173], v[194:197], v[112:115]
	v_mfma_f32_16x16x32_bf16 v[104:107], v[178:181], v[194:197], v[104:107]
	v_mfma_f32_16x16x32_bf16 v[96:99], v[170:173], v[204:207], v[96:99]
	v_mfma_f32_16x16x32_bf16 v[88:91], v[178:181], v[204:207], v[88:91]
	v_mfma_f32_16x16x32_bf16 v[80:83], v[170:173], v[212:215], v[80:83]
	v_mfma_f32_16x16x32_bf16 v[72:75], v[178:181], v[212:215], v[72:75]
	v_mfma_f32_16x16x32_bf16 v[124:127], v[174:177], v[190:193], v[124:127]
	v_mfma_f32_16x16x32_bf16 v[120:123], v[182:185], v[190:193], v[120:123]
	v_mfma_f32_16x16x32_bf16 v[112:115], v[174:177], v[198:201], v[112:115]
	v_mfma_f32_16x16x32_bf16 v[104:107], v[182:185], v[198:201], v[104:107]
	v_mfma_f32_16x16x32_bf16 v[96:99], v[174:177], v[208:211], v[96:99]
	v_mfma_f32_16x16x32_bf16 v[88:91], v[182:185], v[208:211], v[88:91]
	v_mfma_f32_16x16x32_bf16 v[80:83], v[174:177], v[216:219], v[80:83]
	v_mfma_f32_16x16x32_bf16 v[72:75], v[182:185], v[216:219], v[72:75]
	v_mfma_f32_16x16x32_bf16 v[116:119], v[220:223], v[186:189], v[116:119]
	v_mfma_f32_16x16x32_bf16 v[108:111], v[228:231], v[186:189], v[108:111]
	v_mfma_f32_16x16x32_bf16 v[100:103], v[220:223], v[194:197], v[100:103]
	v_mfma_f32_16x16x32_bf16 v[92:95], v[228:231], v[194:197], v[92:95]
	v_mfma_f32_16x16x32_bf16 v[84:87], v[220:223], v[204:207], v[84:87]
	v_mfma_f32_16x16x32_bf16 v[76:79], v[228:231], v[204:207], v[76:79]
	v_mfma_f32_16x16x32_bf16 v[68:71], v[220:223], v[212:215], v[68:71]
	v_mfma_f32_16x16x32_bf16 v[64:67], v[228:231], v[212:215], v[64:67]
	v_mfma_f32_16x16x32_bf16 v[116:119], v[224:227], v[190:193], v[116:119]
	v_mfma_f32_16x16x32_bf16 v[108:111], v[232:235], v[190:193], v[108:111]
	v_mfma_f32_16x16x32_bf16 v[100:103], v[224:227], v[198:201], v[100:103]
	v_mfma_f32_16x16x32_bf16 v[92:95], v[232:235], v[198:201], v[92:95]
	v_mfma_f32_16x16x32_bf16 v[84:87], v[224:227], v[208:211], v[84:87]
	v_mfma_f32_16x16x32_bf16 v[76:79], v[232:235], v[208:211], v[76:79]
	v_mfma_f32_16x16x32_bf16 v[68:71], v[224:227], v[216:219], v[68:71]
	v_mfma_f32_16x16x32_bf16 v[64:67], v[232:235], v[216:219], v[64:67]
	s_setprio 0
	s_barrier
	ds_read_b128 v[186:189], v163 offset:16384
	ds_read_b128 v[190:193], v163 offset:17408
	ds_read_b128 v[194:197], v163 offset:18432
	ds_read_b128 v[198:201], v163 offset:19456
	ds_read_b128 v[204:207], v163 offset:20480
	ds_read_b128 v[208:211], v163 offset:21504
	ds_read_b128 v[212:215], v163 offset:22528
	ds_read_b128 v[216:219], v163 offset:23552
	s_mov_b32 m0, s46
	v_lshl_add_u64 v[144:145], s[34:35], 0, v[128:129]
	global_load_lds_dwordx4 v[144:145], off
	v_lshl_add_u64 v[236:237], s[34:35], 0, v[130:131]
	s_mov_b32 m0, s47
	s_nop 0
	global_load_lds_dwordx4 v[236:237], off
	s_mov_b32 m0, s48
	v_lshl_add_u64 v[238:239], s[36:37], 0, v[128:129]
	global_load_lds_dwordx4 v[238:239], off
	v_lshl_add_u64 v[240:241], s[36:37], 0, v[130:131]
	s_mov_b32 m0, s49
	s_nop 0
	global_load_lds_dwordx4 v[240:241], off
	s_add_u32 s72, s34, 0x40000
	s_addc_u32 s73, s35, 0
	s_mov_b32 m0, s50
	v_lshl_add_u64 v[248:249], s[72:73], 0, v[128:129]
	global_load_lds_dwordx4 v[248:249], off
	v_lshl_add_u64 v[248:249], s[72:73], 0, v[130:131]
	s_mov_b32 m0, s51
	s_nop 0
	global_load_lds_dwordx4 v[248:249], off
	s_waitcnt lgkmcnt(0)
	s_waitcnt vmcnt(8)
	s_barrier
	s_setprio 1
	v_mfma_f32_16x16x32_bf16 v[60:63], v[170:173], v[186:189], v[60:63]
	v_mfma_f32_16x16x32_bf16 v[56:59], v[178:181], v[186:189], v[56:59]
	v_mfma_f32_16x16x32_bf16 v[48:51], v[170:173], v[194:197], v[48:51]
	v_mfma_f32_16x16x32_bf16 v[40:43], v[178:181], v[194:197], v[40:43]
	v_mfma_f32_16x16x32_bf16 v[32:35], v[170:173], v[204:207], v[32:35]
	v_mfma_f32_16x16x32_bf16 v[24:27], v[178:181], v[204:207], v[24:27]
	v_mfma_f32_16x16x32_bf16 v[16:19], v[170:173], v[212:215], v[16:19]
	v_mfma_f32_16x16x32_bf16 v[8:11], v[178:181], v[212:215], v[8:11]
	v_mfma_f32_16x16x32_bf16 v[60:63], v[174:177], v[190:193], v[60:63]
	v_mfma_f32_16x16x32_bf16 v[56:59], v[182:185], v[190:193], v[56:59]
	v_mfma_f32_16x16x32_bf16 v[48:51], v[174:177], v[198:201], v[48:51]
	v_mfma_f32_16x16x32_bf16 v[40:43], v[182:185], v[198:201], v[40:43]
	v_mfma_f32_16x16x32_bf16 v[32:35], v[174:177], v[208:211], v[32:35]
	v_mfma_f32_16x16x32_bf16 v[24:27], v[182:185], v[208:211], v[24:27]
	v_mfma_f32_16x16x32_bf16 v[16:19], v[174:177], v[216:219], v[16:19]
	v_mfma_f32_16x16x32_bf16 v[8:11], v[182:185], v[216:219], v[8:11]
	v_mfma_f32_16x16x32_bf16 v[52:55], v[220:223], v[186:189], v[52:55]
	v_mfma_f32_16x16x32_bf16 v[44:47], v[228:231], v[186:189], v[44:47]
	v_mfma_f32_16x16x32_bf16 v[36:39], v[220:223], v[194:197], v[36:39]
	v_mfma_f32_16x16x32_bf16 v[28:31], v[228:231], v[194:197], v[28:31]
	v_mfma_f32_16x16x32_bf16 v[20:23], v[220:223], v[204:207], v[20:23]
	v_mfma_f32_16x16x32_bf16 v[12:15], v[228:231], v[204:207], v[12:15]
	v_mfma_f32_16x16x32_bf16 v[4:7], v[220:223], v[212:215], v[4:7]
	v_mfma_f32_16x16x32_bf16 v[0:3], v[228:231], v[212:215], v[0:3]
	v_mfma_f32_16x16x32_bf16 v[52:55], v[224:227], v[190:193], v[52:55]
	v_mfma_f32_16x16x32_bf16 v[44:47], v[232:235], v[190:193], v[44:47]
	v_mfma_f32_16x16x32_bf16 v[36:39], v[224:227], v[198:201], v[36:39]
	v_mfma_f32_16x16x32_bf16 v[28:31], v[232:235], v[198:201], v[28:31]
	v_mfma_f32_16x16x32_bf16 v[20:23], v[224:227], v[208:211], v[20:23]
	v_mfma_f32_16x16x32_bf16 v[12:15], v[232:235], v[208:211], v[12:15]
	v_mfma_f32_16x16x32_bf16 v[4:7], v[224:227], v[216:219], v[4:7]
	v_mfma_f32_16x16x32_bf16 v[0:3], v[232:235], v[216:219], v[0:3]
	s_setprio 0
	s_barrier
	ds_read_b128 v[170:173], v165
	ds_read_b128 v[174:177], v165 offset:1024
	ds_read_b128 v[178:181], v165 offset:2048
	ds_read_b128 v[182:185], v165 offset:3072
	s_add_u32 s36, s36, 0x40000
	s_addc_u32 s37, s37, 0
	s_mov_b32 m0, s52
	v_lshl_add_u64 v[220:221], s[36:37], 0, v[128:129]
	ds_read_b128 v[186:189], v163 offset:32768
	ds_read_b128 v[190:193], v163 offset:33792
	ds_read_b128 v[194:197], v163 offset:34816
	ds_read_b128 v[198:201], v163 offset:35840
	ds_read_b128 v[204:207], v163 offset:36864
	ds_read_b128 v[208:211], v163 offset:37888
	ds_read_b128 v[212:215], v163 offset:38912
	ds_read_b128 v[216:219], v163 offset:39936
	global_load_lds_dwordx4 v[220:221], off
	v_lshl_add_u64 v[220:221], s[36:37], 0, v[130:131]
	s_mov_b32 m0, s53
	s_nop 0
	global_load_lds_dwordx4 v[220:221], off
	ds_read_b128 v[220:223], v166
	ds_read_b128 v[224:227], v166 offset:1024
	ds_read_b128 v[228:231], v166 offset:2048
	ds_read_b128 v[232:235], v166 offset:3072
	s_waitcnt lgkmcnt(0)
	s_waitcnt vmcnt(8)
	s_barrier
	s_setprio 1
	v_mfma_f32_16x16x32_bf16 v[124:127], v[170:173], v[186:189], v[124:127]
	v_mfma_f32_16x16x32_bf16 v[120:123], v[178:181], v[186:189], v[120:123]
	v_mfma_f32_16x16x32_bf16 v[112:115], v[170:173], v[194:197], v[112:115]
	v_mfma_f32_16x16x32_bf16 v[104:107], v[178:181], v[194:197], v[104:107]
	v_mfma_f32_16x16x32_bf16 v[96:99], v[170:173], v[204:207], v[96:99]
	v_mfma_f32_16x16x32_bf16 v[88:91], v[178:181], v[204:207], v[88:91]
	v_mfma_f32_16x16x32_bf16 v[80:83], v[170:173], v[212:215], v[80:83]
	v_mfma_f32_16x16x32_bf16 v[72:75], v[178:181], v[212:215], v[72:75]
	v_mfma_f32_16x16x32_bf16 v[124:127], v[174:177], v[190:193], v[124:127]
	v_mfma_f32_16x16x32_bf16 v[120:123], v[182:185], v[190:193], v[120:123]
	v_mfma_f32_16x16x32_bf16 v[112:115], v[174:177], v[198:201], v[112:115]
	v_mfma_f32_16x16x32_bf16 v[104:107], v[182:185], v[198:201], v[104:107]
	v_mfma_f32_16x16x32_bf16 v[96:99], v[174:177], v[208:211], v[96:99]
	v_mfma_f32_16x16x32_bf16 v[88:91], v[182:185], v[208:211], v[88:91]
	v_mfma_f32_16x16x32_bf16 v[80:83], v[174:177], v[216:219], v[80:83]
	v_mfma_f32_16x16x32_bf16 v[72:75], v[182:185], v[216:219], v[72:75]
	v_mfma_f32_16x16x32_bf16 v[116:119], v[220:223], v[186:189], v[116:119]
	v_mfma_f32_16x16x32_bf16 v[108:111], v[228:231], v[186:189], v[108:111]
	v_mfma_f32_16x16x32_bf16 v[100:103], v[220:223], v[194:197], v[100:103]
	v_mfma_f32_16x16x32_bf16 v[92:95], v[228:231], v[194:197], v[92:95]
	v_mfma_f32_16x16x32_bf16 v[84:87], v[220:223], v[204:207], v[84:87]
	v_mfma_f32_16x16x32_bf16 v[76:79], v[228:231], v[204:207], v[76:79]
	v_mfma_f32_16x16x32_bf16 v[68:71], v[220:223], v[212:215], v[68:71]
	v_mfma_f32_16x16x32_bf16 v[64:67], v[228:231], v[212:215], v[64:67]
	v_mfma_f32_16x16x32_bf16 v[116:119], v[224:227], v[190:193], v[116:119]
	v_mfma_f32_16x16x32_bf16 v[108:111], v[232:235], v[190:193], v[108:111]
	v_mfma_f32_16x16x32_bf16 v[100:103], v[224:227], v[198:201], v[100:103]
	v_mfma_f32_16x16x32_bf16 v[92:95], v[232:235], v[198:201], v[92:95]
	v_mfma_f32_16x16x32_bf16 v[84:87], v[224:227], v[208:211], v[84:87]
	v_mfma_f32_16x16x32_bf16 v[76:79], v[232:235], v[208:211], v[76:79]
	v_mfma_f32_16x16x32_bf16 v[68:71], v[224:227], v[216:219], v[68:71]
	v_mfma_f32_16x16x32_bf16 v[64:67], v[232:235], v[216:219], v[64:67]
	s_setprio 0
	s_barrier
	ds_read_b128 v[186:189], v163 offset:49152
	ds_read_b128 v[190:193], v163 offset:50176
	ds_read_b128 v[194:197], v163 offset:51200
	ds_read_b128 v[198:201], v163 offset:52224
	ds_read_b128 v[204:207], v163 offset:53248
	ds_read_b128 v[208:211], v163 offset:54272
	ds_read_b128 v[212:215], v163 offset:55296
	ds_read_b128 v[216:219], v163 offset:56320
	s_mov_b32 m0, s54
	v_lshl_add_u64 v[144:145], v[144:145], 0, s[12:13]
	global_load_lds_dwordx4 v[144:145], off
	v_lshl_add_u64 v[144:145], v[236:237], 0, s[12:13]
	s_mov_b32 m0, s55
	s_nop 0
	global_load_lds_dwordx4 v[144:145], off
	s_mov_b32 m0, s56
	v_lshl_add_u64 v[144:145], v[238:239], 0, s[12:13]
	global_load_lds_dwordx4 v[144:145], off
	v_lshl_add_u64 v[144:145], v[240:241], 0, s[12:13]
	s_mov_b32 m0, s57
	s_nop 0
	global_load_lds_dwordx4 v[144:145], off
	s_add_u32 s34, s34, 0x40080
	s_addc_u32 s35, s35, 0
	s_mov_b32 m0, s58
	v_lshl_add_u64 v[144:145], s[34:35], 0, v[128:129]
	global_load_lds_dwordx4 v[144:145], off
	v_lshl_add_u64 v[144:145], s[34:35], 0, v[130:131]
	s_mov_b32 m0, s59
	s_nop 0
	global_load_lds_dwordx4 v[144:145], off
	s_waitcnt lgkmcnt(0)
	s_waitcnt vmcnt(8)
	s_barrier
	s_setprio 1
	v_mfma_f32_16x16x32_bf16 v[60:63], v[170:173], v[186:189], v[60:63]
	v_mfma_f32_16x16x32_bf16 v[56:59], v[178:181], v[186:189], v[56:59]
	v_mfma_f32_16x16x32_bf16 v[48:51], v[170:173], v[194:197], v[48:51]
	v_mfma_f32_16x16x32_bf16 v[40:43], v[178:181], v[194:197], v[40:43]
	v_mfma_f32_16x16x32_bf16 v[32:35], v[170:173], v[204:207], v[32:35]
	v_mfma_f32_16x16x32_bf16 v[24:27], v[178:181], v[204:207], v[24:27]
	v_mfma_f32_16x16x32_bf16 v[16:19], v[170:173], v[212:215], v[16:19]
	v_mfma_f32_16x16x32_bf16 v[8:11], v[178:181], v[212:215], v[8:11]
	v_mfma_f32_16x16x32_bf16 v[60:63], v[174:177], v[190:193], v[60:63]
	v_mfma_f32_16x16x32_bf16 v[56:59], v[182:185], v[190:193], v[56:59]
	v_mfma_f32_16x16x32_bf16 v[48:51], v[174:177], v[198:201], v[48:51]
	v_mfma_f32_16x16x32_bf16 v[40:43], v[182:185], v[198:201], v[40:43]
	v_mfma_f32_16x16x32_bf16 v[32:35], v[174:177], v[208:211], v[32:35]
	v_mfma_f32_16x16x32_bf16 v[24:27], v[182:185], v[208:211], v[24:27]
	v_mfma_f32_16x16x32_bf16 v[16:19], v[174:177], v[216:219], v[16:19]
	v_mfma_f32_16x16x32_bf16 v[8:11], v[182:185], v[216:219], v[8:11]
	v_mfma_f32_16x16x32_bf16 v[52:55], v[220:223], v[186:189], v[52:55]
	v_mfma_f32_16x16x32_bf16 v[44:47], v[228:231], v[186:189], v[44:47]
	v_mfma_f32_16x16x32_bf16 v[36:39], v[220:223], v[194:197], v[36:39]
	v_mfma_f32_16x16x32_bf16 v[28:31], v[228:231], v[194:197], v[28:31]
	v_mfma_f32_16x16x32_bf16 v[20:23], v[220:223], v[204:207], v[20:23]
	v_mfma_f32_16x16x32_bf16 v[12:15], v[228:231], v[204:207], v[12:15]
	v_mfma_f32_16x16x32_bf16 v[4:7], v[220:223], v[212:215], v[4:7]
	v_mfma_f32_16x16x32_bf16 v[0:3], v[228:231], v[212:215], v[0:3]
	v_mfma_f32_16x16x32_bf16 v[52:55], v[224:227], v[190:193], v[52:55]
	v_mfma_f32_16x16x32_bf16 v[44:47], v[232:235], v[190:193], v[44:47]
	v_mfma_f32_16x16x32_bf16 v[36:39], v[224:227], v[198:201], v[36:39]
	v_mfma_f32_16x16x32_bf16 v[28:31], v[232:235], v[198:201], v[28:31]
	v_mfma_f32_16x16x32_bf16 v[20:23], v[224:227], v[208:211], v[20:23]
	v_mfma_f32_16x16x32_bf16 v[12:15], v[232:235], v[208:211], v[12:15]
	v_mfma_f32_16x16x32_bf16 v[4:7], v[224:227], v[216:219], v[4:7]
	v_mfma_f32_16x16x32_bf16 v[0:3], v[232:235], v[216:219], v[0:3]
	s_setprio 0
	s_add_i32 s41, s41, 2
	s_add_u32 s30, s30, 0x100
	s_addc_u32 s31, s31, 0
	s_add_u32 s39, s39, 0x100
	s_addc_u32 s40, s40, 0
	s_cmp_gt_u32 s41, 13
	s_barrier
	s_cbranch_scc0 .LBB0_1243
	s_cmpk_gt_u32 s33, 0xff
	s_cbranch_scc1 .Lx0_skip
	s_barrier
.Lx0_skip:
	s_cmpk_lt_i32 s42, 0x80
	s_cbranch_scc0 .Lgu_sample
	v_lshlrev_b32_e32 v170, 2, v160
	v_add_u32_e32 v170, s92, v170
	ds_read_b32 v174, v170
	ds_read_b32 v176, v170 offset:64
	ds_read_b32 v156, v170 offset:128
	ds_read_b32 v154, v170 offset:192
	ds_read_b32 v152, v170 offset:512
	ds_read_b32 v150, v170 offset:576
	ds_read_b32 v148, v170 offset:640
	ds_read_b32 v146, v170 offset:704
	v_lshl_add_u32 v144, s42, 8, v160
	v_add_u32_e32 v145, 0x80, v144
	s_cmpk_lt_i32 s42, 0x80
	s_waitcnt lgkmcnt(0)
	v_pk_mul_f32 v[124:125], v[124:125], v[174:175] op_sel_hi:[1,0]
	v_mul_f32_e32 v172, 0xbfb8aa3b, v125
	v_exp_f32_e32 v173, v172
	v_mul_f32_e32 v169, 0xbfb8aa3b, v124
	v_exp_f32_e32 v169, v169
	v_pk_mul_f32 v[126:127], v[126:127], v[174:175] op_sel_hi:[1,0]
	v_pk_mul_f32 v[118:119], v[118:119], v[174:175] op_sel_hi:[1,0]
	v_add_f32_e32 v169, 1.0, v169
	v_rcp_f32_e32 v172, v169
	v_add_f32_e32 v169, 1.0, v173
	v_mul_f32_e32 v173, 0xbfb8aa3b, v126
	v_exp_f32_e32 v175, v173
	v_mul_f32_e32 v173, 0xbfb8aa3b, v127
	v_exp_f32_e32 v177, v173
	v_rcp_f32_e32 v173, v169
	v_add_f32_e32 v169, 1.0, v175
	v_rcp_f32_e32 v178, v169
	v_add_f32_e32 v169, 1.0, v177
	v_rcp_f32_e32 v179, v169
	v_pk_mul_f32 v[116:117], v[116:117], v[174:175] op_sel_hi:[1,0]
	v_pk_mul_f32 v[124:125], v[124:125], v[172:173]
	v_pk_mul_f32 v[120:121], v[120:121], v[174:175] op_sel_hi:[1,0]
	v_pk_mul_f32 v[116:117], v[116:117], v[124:125]
	v_pk_mul_f32 v[124:125], v[126:127], v[178:179]
	v_pk_mul_f32 v[122:123], v[122:123], v[174:175] op_sel_hi:[1,0]
	v_pk_mul_f32 v[118:119], v[118:119], v[124:125]
	v_mul_f32_e32 v124, 0xbfb8aa3b, v120
	v_mul_f32_e32 v125, 0xbfb8aa3b, v121
	v_exp_f32_e32 v124, v124
	v_exp_f32_e32 v125, v125
	v_mul_f32_e32 v126, 0xbfb8aa3b, v122
	v_mul_f32_e32 v127, 0xbfb8aa3b, v123
	v_exp_f32_e32 v126, v126
	v_exp_f32_e32 v127, v127
	v_add_f32_e32 v124, 1.0, v124
	v_add_f32_e32 v125, 1.0, v125
	v_rcp_f32_e32 v124, v124
	v_rcp_f32_e32 v125, v125
	v_add_f32_e32 v126, 1.0, v126
	v_add_f32_e32 v127, 1.0, v127
	v_rcp_f32_e32 v126, v126
	v_rcp_f32_e32 v127, v127
	v_pk_mul_f32 v[108:109], v[108:109], v[174:175] op_sel_hi:[1,0]
	v_pk_mul_f32 v[120:121], v[120:121], v[124:125]
	v_lshl_or_b32 v170, s28, 7, v161
	v_pk_mul_f32 v[110:111], v[110:111], v[174:175] op_sel_hi:[1,0]
	v_pk_mul_f32 v[108:109], v[108:109], v[120:121]
	v_pk_mul_f32 v[120:121], v[122:123], v[126:127]
	v_ashrrev_i32_e32 v171, 31, v170
	v_pk_mul_f32 v[110:111], v[110:111], v[120:121]
	v_cvt_pk_bf16_f32 v116, v116, v117
	v_cvt_pk_bf16_f32 v117, v118, v119
	v_cvt_pk_bf16_f32 v118, v108, v109
	v_mov_b64_e32 v[108:109], s[6:7]
	v_cvt_pk_bf16_f32 v119, v110, v111
	v_mad_i64_i32 v[120:121], s[28:29], v144, s68, v[108:109]
	v_lshlrev_b64 v[110:111], 1, v[170:171]
	v_lshl_add_u64 v[120:121], v[120:121], 0, v[110:111]
	v_pk_mul_f32 v[112:113], v[112:113], v[176:177] op_sel_hi:[1,0]
	global_store_dwordx4 v[120:121], v[116:119], off
	v_pk_mul_f32 v[114:115], v[114:115], v[176:177] op_sel_hi:[1,0]
	v_pk_mul_f32 v[100:101], v[100:101], v[176:177] op_sel_hi:[1,0]
	v_mul_f32_e32 v116, 0xbfb8aa3b, v112
	v_mul_f32_e32 v117, 0xbfb8aa3b, v113
	v_exp_f32_e32 v116, v116
	v_exp_f32_e32 v117, v117
	v_mul_f32_e32 v118, 0xbfb8aa3b, v114
	v_mul_f32_e32 v119, 0xbfb8aa3b, v115
	v_exp_f32_e32 v118, v118
	v_exp_f32_e32 v119, v119
	v_add_f32_e32 v116, 1.0, v116
	v_add_f32_e32 v117, 1.0, v117
	v_rcp_f32_e32 v116, v116
	v_rcp_f32_e32 v117, v117
	v_add_f32_e32 v118, 1.0, v118
	v_add_f32_e32 v119, 1.0, v119
	v_rcp_f32_e32 v118, v118
	v_rcp_f32_e32 v119, v119
	v_pk_mul_f32 v[112:113], v[112:113], v[116:117]
	v_pk_mul_f32 v[102:103], v[102:103], v[176:177] op_sel_hi:[1,0]
	v_pk_mul_f32 v[100:101], v[100:101], v[112:113]
	v_pk_mul_f32 v[112:113], v[114:115], v[118:119]
	v_pk_mul_f32 v[104:105], v[104:105], v[176:177] op_sel_hi:[1,0]
	v_pk_mul_f32 v[102:103], v[102:103], v[112:113]
	v_pk_mul_f32 v[106:107], v[106:107], v[176:177] op_sel_hi:[1,0]
	v_mul_f32_e32 v112, 0xbfb8aa3b, v104
	v_mul_f32_e32 v113, 0xbfb8aa3b, v105
	v_exp_f32_e32 v112, v112
	v_exp_f32_e32 v113, v113
	v_mul_f32_e32 v114, 0xbfb8aa3b, v106
	v_mul_f32_e32 v115, 0xbfb8aa3b, v107
	v_exp_f32_e32 v114, v114
	v_exp_f32_e32 v115, v115
	v_add_f32_e32 v112, 1.0, v112
	v_add_f32_e32 v113, 1.0, v113
	v_rcp_f32_e32 v112, v112
	v_rcp_f32_e32 v113, v113
	v_add_f32_e32 v114, 1.0, v114
	v_add_f32_e32 v115, 1.0, v115
	v_rcp_f32_e32 v114, v114
	v_rcp_f32_e32 v115, v115
	v_pk_mul_f32 v[92:93], v[92:93], v[176:177] op_sel_hi:[1,0]
	v_pk_mul_f32 v[104:105], v[104:105], v[112:113]
	v_pk_mul_f32 v[94:95], v[94:95], v[176:177] op_sel_hi:[1,0]
	v_pk_mul_f32 v[104:105], v[92:93], v[104:105]
	v_pk_mul_f32 v[92:93], v[106:107], v[114:115]
	v_or_b32_e32 v112, 16, v144
	v_pk_mul_f32 v[106:107], v[94:95], v[92:93]
	v_cvt_pk_bf16_f32 v92, v100, v101
	v_mad_i64_i32 v[100:101], s[28:29], v112, s68, v[108:109]
	v_cvt_pk_bf16_f32 v93, v102, v103
	v_cvt_pk_bf16_f32 v94, v104, v105
	v_cvt_pk_bf16_f32 v95, v106, v107
	v_lshl_add_u64 v[100:101], v[100:101], 0, v[110:111]
	global_store_dwordx4 v[100:101], v[92:95], off
	v_pk_mul_f32 v[86:87], v[86:87], v[156:157] op_sel_hi:[1,0]
	v_pk_mul_f32 v[88:89], v[88:89], v[156:157] op_sel_hi:[1,0]
	v_pk_mul_f32 v[92:93], v[98:99], v[156:157] op_sel_hi:[1,0]
	v_pk_mul_f32 v[94:95], v[96:97], v[156:157] op_sel_hi:[1,0]
	v_mul_f32_e32 v98, 0xbfb8aa3b, v92
	v_mul_f32_e32 v99, 0xbfb8aa3b, v93
	v_mul_f32_e32 v96, 0xbfb8aa3b, v94
	v_mul_f32_e32 v97, 0xbfb8aa3b, v95
	v_exp_f32_e32 v98, v98
	v_exp_f32_e32 v99, v99
	v_exp_f32_e32 v96, v96
	v_exp_f32_e32 v97, v97
	v_add_f32_e32 v98, 1.0, v98
	v_add_f32_e32 v99, 1.0, v99
	v_add_f32_e32 v96, 1.0, v96
	v_add_f32_e32 v97, 1.0, v97
	v_rcp_f32_e32 v98, v98
	v_rcp_f32_e32 v99, v99
	v_rcp_f32_e32 v96, v96
	v_rcp_f32_e32 v97, v97
	v_pk_mul_f32 v[84:85], v[84:85], v[156:157] op_sel_hi:[1,0]
	v_pk_mul_f32 v[92:93], v[92:93], v[98:99]
	v_pk_mul_f32 v[90:91], v[90:91], v[156:157] op_sel_hi:[1,0]
	v_pk_mul_f32 v[94:95], v[94:95], v[96:97]
	v_pk_mul_f32 v[86:87], v[86:87], v[92:93]
	v_mul_f32_e32 v92, 0xbfb8aa3b, v88
	v_mul_f32_e32 v93, 0xbfb8aa3b, v89
	v_pk_mul_f32 v[84:85], v[84:85], v[94:95]
	v_exp_f32_e32 v92, v92
	v_exp_f32_e32 v93, v93
	v_mul_f32_e32 v94, 0xbfb8aa3b, v90
	v_mul_f32_e32 v95, 0xbfb8aa3b, v91
	v_exp_f32_e32 v94, v94
	v_exp_f32_e32 v95, v95
	v_add_f32_e32 v92, 1.0, v92
	v_add_f32_e32 v93, 1.0, v93
	v_rcp_f32_e32 v92, v92
	v_rcp_f32_e32 v93, v93
	v_add_f32_e32 v94, 1.0, v94
	v_add_f32_e32 v95, 1.0, v95
	v_rcp_f32_e32 v94, v94
	v_rcp_f32_e32 v95, v95
	v_pk_mul_f32 v[76:77], v[76:77], v[156:157] op_sel_hi:[1,0]
	v_pk_mul_f32 v[88:89], v[88:89], v[92:93]
	v_pk_mul_f32 v[78:79], v[78:79], v[156:157] op_sel_hi:[1,0]
	v_pk_mul_f32 v[88:89], v[76:77], v[88:89]
	v_pk_mul_f32 v[76:77], v[90:91], v[94:95]
	v_or_b32_e32 v92, 32, v144
	v_pk_mul_f32 v[90:91], v[78:79], v[76:77]
	v_cvt_pk_bf16_f32 v76, v84, v85
	v_mad_i64_i32 v[84:85], s[28:29], v92, s68, v[108:109]
	v_cvt_pk_bf16_f32 v77, v86, v87
	v_cvt_pk_bf16_f32 v78, v88, v89
	v_cvt_pk_bf16_f32 v79, v90, v91
	v_lshl_add_u64 v[84:85], v[84:85], 0, v[110:111]
	global_store_dwordx4 v[84:85], v[76:79], off
	v_pk_mul_f32 v[70:71], v[70:71], v[154:155] op_sel_hi:[1,0]
	v_pk_mul_f32 v[72:73], v[72:73], v[154:155] op_sel_hi:[1,0]
	v_pk_mul_f32 v[76:77], v[82:83], v[154:155] op_sel_hi:[1,0]
	v_pk_mul_f32 v[78:79], v[80:81], v[154:155] op_sel_hi:[1,0]
	v_mul_f32_e32 v82, 0xbfb8aa3b, v76
	v_mul_f32_e32 v83, 0xbfb8aa3b, v77
	v_mul_f32_e32 v80, 0xbfb8aa3b, v78
	v_mul_f32_e32 v81, 0xbfb8aa3b, v79
	v_exp_f32_e32 v82, v82
	v_exp_f32_e32 v83, v83
	v_exp_f32_e32 v80, v80
	v_exp_f32_e32 v81, v81
	v_add_f32_e32 v82, 1.0, v82
	v_add_f32_e32 v83, 1.0, v83
	v_add_f32_e32 v80, 1.0, v80
	v_add_f32_e32 v81, 1.0, v81
	v_rcp_f32_e32 v82, v82
	v_rcp_f32_e32 v83, v83
	v_rcp_f32_e32 v80, v80
	v_rcp_f32_e32 v81, v81
	v_pk_mul_f32 v[68:69], v[68:69], v[154:155] op_sel_hi:[1,0]
	v_pk_mul_f32 v[76:77], v[76:77], v[82:83]
	v_pk_mul_f32 v[74:75], v[74:75], v[154:155] op_sel_hi:[1,0]
	v_pk_mul_f32 v[78:79], v[78:79], v[80:81]
	v_pk_mul_f32 v[70:71], v[70:71], v[76:77]
	v_mul_f32_e32 v76, 0xbfb8aa3b, v72
	v_mul_f32_e32 v77, 0xbfb8aa3b, v73
	v_pk_mul_f32 v[68:69], v[68:69], v[78:79]
	v_exp_f32_e32 v76, v76
	v_exp_f32_e32 v77, v77
	v_mul_f32_e32 v78, 0xbfb8aa3b, v74
	v_mul_f32_e32 v79, 0xbfb8aa3b, v75
	v_exp_f32_e32 v78, v78
	v_exp_f32_e32 v79, v79
	v_add_f32_e32 v76, 1.0, v76
	v_add_f32_e32 v77, 1.0, v77
	v_rcp_f32_e32 v76, v76
	v_rcp_f32_e32 v77, v77
	v_add_f32_e32 v78, 1.0, v78
	v_add_f32_e32 v79, 1.0, v79
	v_rcp_f32_e32 v78, v78
	v_rcp_f32_e32 v79, v79
	v_pk_mul_f32 v[64:65], v[64:65], v[154:155] op_sel_hi:[1,0]
	v_pk_mul_f32 v[72:73], v[72:73], v[76:77]
	v_pk_mul_f32 v[66:67], v[66:67], v[154:155] op_sel_hi:[1,0]
	v_pk_mul_f32 v[72:73], v[64:65], v[72:73]
	v_pk_mul_f32 v[64:65], v[74:75], v[78:79]
	v_or_b32_e32 v76, 48, v144
	v_pk_mul_f32 v[74:75], v[66:67], v[64:65]
	v_cvt_pk_bf16_f32 v64, v68, v69
	v_mad_i64_i32 v[68:69], s[28:29], v76, s68, v[108:109]
	v_cvt_pk_bf16_f32 v65, v70, v71
	v_cvt_pk_bf16_f32 v66, v72, v73
	v_cvt_pk_bf16_f32 v67, v74, v75
	v_lshl_add_u64 v[68:69], v[68:69], 0, v[110:111]
	v_pk_mul_f32 v[60:61], v[60:61], v[152:153] op_sel_hi:[1,0]
	global_store_dwordx4 v[68:69], v[64:67], off
	v_pk_mul_f32 v[62:63], v[62:63], v[152:153] op_sel_hi:[1,0]
	v_pk_mul_f32 v[52:53], v[52:53], v[152:153] op_sel_hi:[1,0]
	v_mul_f32_e32 v64, 0xbfb8aa3b, v60
	v_mul_f32_e32 v65, 0xbfb8aa3b, v61
	v_exp_f32_e32 v64, v64
	v_exp_f32_e32 v65, v65
	v_mul_f32_e32 v66, 0xbfb8aa3b, v62
	v_mul_f32_e32 v67, 0xbfb8aa3b, v63
	v_exp_f32_e32 v66, v66
	v_exp_f32_e32 v67, v67
	v_add_f32_e32 v64, 1.0, v64
	v_add_f32_e32 v65, 1.0, v65
	v_rcp_f32_e32 v64, v64
	v_rcp_f32_e32 v65, v65
	v_add_f32_e32 v66, 1.0, v66
	v_add_f32_e32 v67, 1.0, v67
	v_rcp_f32_e32 v66, v66
	v_rcp_f32_e32 v67, v67
	v_pk_mul_f32 v[60:61], v[60:61], v[64:65]
	v_pk_mul_f32 v[54:55], v[54:55], v[152:153] op_sel_hi:[1,0]
	v_pk_mul_f32 v[52:53], v[52:53], v[60:61]
	v_pk_mul_f32 v[60:61], v[62:63], v[66:67]
	v_pk_mul_f32 v[56:57], v[56:57], v[152:153] op_sel_hi:[1,0]
	v_pk_mul_f32 v[54:55], v[54:55], v[60:61]
	v_pk_mul_f32 v[58:59], v[58:59], v[152:153] op_sel_hi:[1,0]
	v_mul_f32_e32 v60, 0xbfb8aa3b, v56
	v_mul_f32_e32 v61, 0xbfb8aa3b, v57
	v_exp_f32_e32 v60, v60
	v_exp_f32_e32 v61, v61
	v_mul_f32_e32 v62, 0xbfb8aa3b, v58
	v_mul_f32_e32 v63, 0xbfb8aa3b, v59
	v_exp_f32_e32 v62, v62
	v_exp_f32_e32 v63, v63
	v_add_f32_e32 v60, 1.0, v60
	v_add_f32_e32 v61, 1.0, v61
	v_rcp_f32_e32 v60, v60
	v_rcp_f32_e32 v61, v61
	v_add_f32_e32 v62, 1.0, v62
	v_add_f32_e32 v63, 1.0, v63
	v_rcp_f32_e32 v62, v62
	v_rcp_f32_e32 v63, v63
	v_pk_mul_f32 v[44:45], v[44:45], v[152:153] op_sel_hi:[1,0]
	v_pk_mul_f32 v[56:57], v[56:57], v[60:61]
	v_pk_mul_f32 v[46:47], v[46:47], v[152:153] op_sel_hi:[1,0]
	v_pk_mul_f32 v[56:57], v[44:45], v[56:57]
	v_pk_mul_f32 v[44:45], v[58:59], v[62:63]
	v_pk_mul_f32 v[38:39], v[38:39], v[150:151] op_sel_hi:[1,0]
	v_pk_mul_f32 v[58:59], v[46:47], v[44:45]
	v_cvt_pk_bf16_f32 v44, v52, v53
	v_mad_i64_i32 v[52:53], s[28:29], v145, s68, v[108:109]
	v_cvt_pk_bf16_f32 v45, v54, v55
	v_cvt_pk_bf16_f32 v46, v56, v57
	v_cvt_pk_bf16_f32 v47, v58, v59
	v_lshl_add_u64 v[52:53], v[52:53], 0, v[110:111]
	global_store_dwordx4 v[52:53], v[44:47], off
	v_pk_mul_f32 v[40:41], v[40:41], v[150:151] op_sel_hi:[1,0]
	v_pk_mul_f32 v[36:37], v[36:37], v[150:151] op_sel_hi:[1,0]
	v_pk_mul_f32 v[44:45], v[50:51], v[150:151] op_sel_hi:[1,0]
	v_pk_mul_f32 v[46:47], v[48:49], v[150:151] op_sel_hi:[1,0]
	v_mul_f32_e32 v50, 0xbfb8aa3b, v44
	v_mul_f32_e32 v51, 0xbfb8aa3b, v45
	v_mul_f32_e32 v48, 0xbfb8aa3b, v46
	v_mul_f32_e32 v49, 0xbfb8aa3b, v47
	v_exp_f32_e32 v50, v50
	v_exp_f32_e32 v51, v51
	v_exp_f32_e32 v48, v48
	v_exp_f32_e32 v49, v49
	v_add_f32_e32 v50, 1.0, v50
	v_add_f32_e32 v51, 1.0, v51
	v_add_f32_e32 v48, 1.0, v48
	v_add_f32_e32 v49, 1.0, v49
	v_rcp_f32_e32 v50, v50
	v_rcp_f32_e32 v51, v51
	v_rcp_f32_e32 v48, v48
	v_rcp_f32_e32 v49, v49
	v_pk_mul_f32 v[42:43], v[42:43], v[150:151] op_sel_hi:[1,0]
	v_pk_mul_f32 v[44:45], v[44:45], v[50:51]
	v_pk_mul_f32 v[46:47], v[46:47], v[48:49]
	v_pk_mul_f32 v[38:39], v[38:39], v[44:45]
	v_mul_f32_e32 v44, 0xbfb8aa3b, v40
	v_mul_f32_e32 v45, 0xbfb8aa3b, v41
	v_pk_mul_f32 v[36:37], v[36:37], v[46:47]
	v_exp_f32_e32 v44, v44
	v_exp_f32_e32 v45, v45
	v_mul_f32_e32 v46, 0xbfb8aa3b, v42
	v_mul_f32_e32 v47, 0xbfb8aa3b, v43
	v_exp_f32_e32 v46, v46
	v_exp_f32_e32 v47, v47
	v_add_f32_e32 v44, 1.0, v44
	v_add_f32_e32 v45, 1.0, v45
	v_rcp_f32_e32 v44, v44
	v_rcp_f32_e32 v45, v45
	v_add_f32_e32 v46, 1.0, v46
	v_add_f32_e32 v47, 1.0, v47
	v_rcp_f32_e32 v46, v46
	v_rcp_f32_e32 v47, v47
	v_pk_mul_f32 v[28:29], v[28:29], v[150:151] op_sel_hi:[1,0]
	v_pk_mul_f32 v[40:41], v[40:41], v[44:45]
	v_pk_mul_f32 v[30:31], v[30:31], v[150:151] op_sel_hi:[1,0]
	v_pk_mul_f32 v[40:41], v[28:29], v[40:41]
	v_pk_mul_f32 v[28:29], v[42:43], v[46:47]
	v_add_u32_e32 v44, 0x90, v144
	v_pk_mul_f32 v[42:43], v[30:31], v[28:29]
	v_cvt_pk_bf16_f32 v28, v36, v37
	v_mad_i64_i32 v[36:37], s[28:29], v44, s68, v[108:109]
	v_cvt_pk_bf16_f32 v29, v38, v39
	v_cvt_pk_bf16_f32 v30, v40, v41
	v_cvt_pk_bf16_f32 v31, v42, v43
	v_lshl_add_u64 v[36:37], v[36:37], 0, v[110:111]
	global_store_dwordx4 v[36:37], v[28:31], off
	v_pk_mul_f32 v[22:23], v[22:23], v[148:149] op_sel_hi:[1,0]
	v_pk_mul_f32 v[24:25], v[24:25], v[148:149] op_sel_hi:[1,0]
	v_pk_mul_f32 v[28:29], v[34:35], v[148:149] op_sel_hi:[1,0]
	v_pk_mul_f32 v[30:31], v[32:33], v[148:149] op_sel_hi:[1,0]
	v_mul_f32_e32 v34, 0xbfb8aa3b, v28
	v_mul_f32_e32 v35, 0xbfb8aa3b, v29
	v_mul_f32_e32 v32, 0xbfb8aa3b, v30
	v_mul_f32_e32 v33, 0xbfb8aa3b, v31
	v_exp_f32_e32 v34, v34
	v_exp_f32_e32 v35, v35
	v_exp_f32_e32 v32, v32
	v_exp_f32_e32 v33, v33
	v_add_f32_e32 v34, 1.0, v34
	v_add_f32_e32 v35, 1.0, v35
	v_add_f32_e32 v32, 1.0, v32
	v_add_f32_e32 v33, 1.0, v33
	v_rcp_f32_e32 v34, v34
	v_rcp_f32_e32 v35, v35
	v_rcp_f32_e32 v32, v32
	v_rcp_f32_e32 v33, v33
	v_pk_mul_f32 v[20:21], v[20:21], v[148:149] op_sel_hi:[1,0]
	v_pk_mul_f32 v[28:29], v[28:29], v[34:35]
	v_pk_mul_f32 v[26:27], v[26:27], v[148:149] op_sel_hi:[1,0]
	v_pk_mul_f32 v[30:31], v[30:31], v[32:33]
	v_pk_mul_f32 v[22:23], v[22:23], v[28:29]
	v_mul_f32_e32 v28, 0xbfb8aa3b, v24
	v_mul_f32_e32 v29, 0xbfb8aa3b, v25
	v_pk_mul_f32 v[20:21], v[20:21], v[30:31]
	v_exp_f32_e32 v28, v28
	v_exp_f32_e32 v29, v29
	v_mul_f32_e32 v30, 0xbfb8aa3b, v26
	v_mul_f32_e32 v31, 0xbfb8aa3b, v27
	v_exp_f32_e32 v30, v30
	v_exp_f32_e32 v31, v31
	v_add_f32_e32 v28, 1.0, v28
	v_add_f32_e32 v29, 1.0, v29
	v_rcp_f32_e32 v28, v28
	v_rcp_f32_e32 v29, v29
	v_add_f32_e32 v30, 1.0, v30
	v_add_f32_e32 v31, 1.0, v31
	v_rcp_f32_e32 v30, v30
	v_rcp_f32_e32 v31, v31
	v_pk_mul_f32 v[12:13], v[12:13], v[148:149] op_sel_hi:[1,0]
	v_pk_mul_f32 v[24:25], v[24:25], v[28:29]
	v_pk_mul_f32 v[14:15], v[14:15], v[148:149] op_sel_hi:[1,0]
	v_pk_mul_f32 v[24:25], v[12:13], v[24:25]
	v_pk_mul_f32 v[12:13], v[26:27], v[30:31]
	v_add_u32_e32 v28, 0xa0, v144
	v_pk_mul_f32 v[26:27], v[14:15], v[12:13]
	v_cvt_pk_bf16_f32 v12, v20, v21
	v_mad_i64_i32 v[20:21], s[28:29], v28, s68, v[108:109]
	v_cvt_pk_bf16_f32 v13, v22, v23
	v_cvt_pk_bf16_f32 v14, v24, v25
	v_cvt_pk_bf16_f32 v15, v26, v27
	v_lshl_add_u64 v[20:21], v[20:21], 0, v[110:111]
	global_store_dwordx4 v[20:21], v[12:15], off
	v_pk_mul_f32 v[6:7], v[6:7], v[146:147] op_sel_hi:[1,0]
	v_pk_mul_f32 v[8:9], v[8:9], v[146:147] op_sel_hi:[1,0]
	v_pk_mul_f32 v[12:13], v[18:19], v[146:147] op_sel_hi:[1,0]
	v_pk_mul_f32 v[14:15], v[16:17], v[146:147] op_sel_hi:[1,0]
	v_mul_f32_e32 v18, 0xbfb8aa3b, v12
	v_mul_f32_e32 v19, 0xbfb8aa3b, v13
	v_mul_f32_e32 v16, 0xbfb8aa3b, v14
	v_mul_f32_e32 v17, 0xbfb8aa3b, v15
	v_exp_f32_e32 v18, v18
	v_exp_f32_e32 v19, v19
	v_exp_f32_e32 v16, v16
	v_exp_f32_e32 v17, v17
	v_add_f32_e32 v18, 1.0, v18
	v_add_f32_e32 v19, 1.0, v19
	v_add_f32_e32 v16, 1.0, v16
	v_add_f32_e32 v17, 1.0, v17
	v_rcp_f32_e32 v18, v18
	v_rcp_f32_e32 v19, v19
	v_rcp_f32_e32 v16, v16
	v_rcp_f32_e32 v17, v17
	v_pk_mul_f32 v[4:5], v[4:5], v[146:147] op_sel_hi:[1,0]
	v_pk_mul_f32 v[12:13], v[12:13], v[18:19]
	v_pk_mul_f32 v[10:11], v[10:11], v[146:147] op_sel_hi:[1,0]
	v_pk_mul_f32 v[14:15], v[14:15], v[16:17]
	v_pk_mul_f32 v[6:7], v[6:7], v[12:13]
	v_mul_f32_e32 v12, 0xbfb8aa3b, v8
	v_mul_f32_e32 v13, 0xbfb8aa3b, v9
	v_pk_mul_f32 v[4:5], v[4:5], v[14:15]
	v_exp_f32_e32 v12, v12
	v_exp_f32_e32 v13, v13
	v_mul_f32_e32 v14, 0xbfb8aa3b, v10
	v_mul_f32_e32 v15, 0xbfb8aa3b, v11
	v_exp_f32_e32 v14, v14
	v_exp_f32_e32 v15, v15
	v_add_f32_e32 v12, 1.0, v12
	v_add_f32_e32 v13, 1.0, v13
	v_rcp_f32_e32 v12, v12
	v_rcp_f32_e32 v13, v13
	v_add_f32_e32 v14, 1.0, v14
	v_add_f32_e32 v15, 1.0, v15
	v_rcp_f32_e32 v14, v14
	v_rcp_f32_e32 v15, v15
	v_pk_mul_f32 v[0:1], v[0:1], v[146:147] op_sel_hi:[1,0]
	v_pk_mul_f32 v[8:9], v[8:9], v[12:13]
	v_pk_mul_f32 v[2:3], v[2:3], v[146:147] op_sel_hi:[1,0]
	v_pk_mul_f32 v[8:9], v[0:1], v[8:9]
	v_pk_mul_f32 v[0:1], v[10:11], v[14:15]
	v_add_u32_e32 v12, 0xb0, v144
	v_pk_mul_f32 v[10:11], v[2:3], v[0:1]
	v_cvt_pk_bf16_f32 v0, v4, v5
	v_mad_i64_i32 v[4:5], s[28:29], v12, s68, v[108:109]
	v_cvt_pk_bf16_f32 v1, v6, v7
	v_cvt_pk_bf16_f32 v2, v8, v9
	v_cvt_pk_bf16_f32 v3, v10, v11
	v_lshl_add_u64 v[4:5], v[4:5], 0, v[110:111]
	global_store_dwordx4 v[4:5], v[0:3], off
	s_cbranch_scc1 .LBB0_1226
	s_waitcnt vmcnt(0)
	buffer_wbl2 sc1
	s_waitcnt vmcnt(0)
	s_waitcnt vmcnt(0)
	s_and_saveexec_b64 s[28:29], s[4:5]
	s_cbranch_execz .LBB0_1225
	s_mov_b64 s[30:31], exec
	v_mbcnt_lo_u32_b32 v0, s30, 0
	v_mbcnt_hi_u32_b32 v0, s31, v0
	v_cmp_eq_u32_e32 vcc, 0, v0
	s_and_b64 s[34:35], exec, vcc
	s_mov_b64 exec, s[34:35]
	s_cbranch_execz .LBB0_1225
	s_bcnt1_i32_b64 s11, s[30:31]
	v_mov_b32_e32 v0, s11
	global_atomic_add v129, v0, s[8:9]
	s_branch .LBB0_1225

.LBB0_1248:
	s_waitcnt vmcnt(0)
	s_cmpk_gt_u32 s33, 0xff
	s_cbranch_scc1 .LBB0_1250
	s_nop 0
